# MFMA order inside each 8-group changed to hold the B-fragment operand for 4 consecutive MFMAs (bit-identical accumulation order), on top of the aligned loop heads
# baseline (speedup 1.0000x reference)
; #define PG8_STAGE(bufoff, gbase, voff) do { _Pragma("unroll") for (int _i = 0; _i < 2; ++_i) \
;         __builtin_amdgcn_global_load_lds((const unsigned*)((const char*)(gbase) + (voff)[_i]), (LAS unsigned*)(lds + (bufoff) + ldsw + _i * 8192), 16, 0, 0); } while (0)
; #define PG8_LDA(dst, b, h) do { _Pragma("unroll") for (int m = 0; m < 4; ++m) _Pragma("unroll") for (int k = 0; k < 2; ++k) dst[m][k] = *(const LAS bf16x8*)(lds + PG8_SA(b, h) + aoff + m * 2048 + k * 1024); } while (0)
; #define PG8_LDB(dst, b, h) do { _Pragma("unroll") for (int n = 0; n < 2; ++n) _Pragma("unroll") for (int k = 0; k < 2; ++k) dst[n][k] = *(const LAS bf16x8*)(lds + PG8_SB(b, h) + boff + n * 2048 + k * 1024); } while (0)
; #define PG8_MMA(ai, bj, At, Bt) do { __builtin_amdgcn_s_setprio(1); _Pragma("unroll") for (int m = 0; m < 4; ++m) _Pragma("unroll") for (int n = 0; n < 2; ++n) _Pragma("unroll") for (int k = 0; k < 2; ++k) \
;         acc[ai][bj][m][n] = __builtin_amdgcn_mfma_f32_16x16x32_bf16(Bt[n][k], At[m][k], acc[ai][bj][m][n], 0, 0, 0); __builtin_amdgcn_s_setprio(0); } while (0)
; #define PG8_WAIT_V(n) asm volatile("s_waitcnt vmcnt(" #n ")" ::: "memory")
; #define PG8_WAIT_L(n) asm volatile("s_waitcnt lgkmcnt(" #n ")" ::: "memory")
; #define PG8_BAR __builtin_amdgcn_s_barrier()
; #define PG8_SCHED __builtin_amdgcn_sched_barrier(0)
; template <class Epi, class Sched>
; __device__ __forceinline__ void gemm_phase(LAS unsigned char* lds, const Gemm g, const Sched& S, const Epi& E) {
;     ...
;             PG8_LDB(B0, 0, 0); PG8_LDB(B1, 0, 1); PG8_SCHED; PG8_LDA(At, 0, 0); PG8_STAGE(PG8_SA(1, 1), a1 + hstep, voffA);
;             PG8_WAIT_V(8); PG8_WAIT_L(0); PG8_BAR; PG8_MMA(0, 0, At, B0); PG8_MMA(0, 1, At, B1); PG8_BAR; PG8_SCHED;
;             PG8_LDA(At, 0, 1); PG8_STAGE(PG8_SB(0, 0), b2, voffB); PG8_STAGE(PG8_SB(0, 1), b2 + hstep, voffB); PG8_STAGE(PG8_SA(0, 0), a2, voffA);
;             PG8_WAIT_V(8); PG8_WAIT_L(0); PG8_BAR; PG8_MMA(1, 0, At, B0); PG8_MMA(1, 1, At, B1); PG8_BAR; PG8_SCHED;
.LBB0_503:
	s_add_u32 s16, s14, 0xfffc0080
	s_addc_u32 s17, s15, -1
	s_add_i32 s41, 0, 0x10000
	s_cmp_eq_u32 s40, 12
	s_cselect_b32 s19, s7, s17
	s_cselect_b32 s18, s8, s16
	s_cselect_b32 s17, s12, s33
	s_cselect_b32 s16, s13, s21
	s_add_i32 s51, 0, 0x14000
	v_add_u32_e32 v84, s41, v168
	v_add_u32_e32 v170, s51, v168
	ds_read_b128 v[72:75], v84
	ds_read_b128 v[76:79], v84 offset:1024
	ds_read_b128 v[80:83], v84 offset:2048
	ds_read_b128 v[84:87], v84 offset:3072
	ds_read_b128 v[154:157], v170
	ds_read_b128 v[158:161], v170 offset:1024
	ds_read_b128 v[162:165], v170 offset:2048
	ds_read_b128 v[170:173], v170 offset:3072
	v_lshl_add_u64 v[178:179], s[14:15], 0, v[150:151]
	s_add_i32 m0, s26, 0xc000
	ds_read_b128 v[174:177], v169
	ds_read_b128 v[192:195], v169 offset:1024
	ds_read_b128 v[196:199], v169 offset:2048
	ds_read_b128 v[200:203], v169 offset:3072
	ds_read_b128 v[204:207], v169 offset:4096
	ds_read_b128 v[208:211], v169 offset:5120
	ds_read_b128 v[212:215], v169 offset:6144
	ds_read_b128 v[230:233], v169 offset:7168
	global_load_lds_dwordx4 v[178:179], off
	v_lshl_add_u64 v[178:179], s[14:15], 0, v[152:153]
	s_add_i32 m0, s26, 0xe000
	s_nop 0
	global_load_lds_dwordx4 v[178:179], off
	s_waitcnt vmcnt(8)
	s_waitcnt lgkmcnt(0)
	s_barrier
	s_setprio 1
	s_waitcnt lgkmcnt(0)
	v_mfma_f32_16x16x32_bf16 v[140:143], v[72:75], v[174:177], v[140:143]
	v_mfma_f32_16x16x32_bf16 v[124:127], v[72:75], v[196:199], v[124:127]
	v_mfma_f32_16x16x32_bf16 v[108:111], v[72:75], v[204:207], v[108:111]
	v_mfma_f32_16x16x32_bf16 v[92:95], v[72:75], v[212:215], v[92:95]
	v_mfma_f32_16x16x32_bf16 v[136:139], v[80:83], v[174:177], v[136:139]
	v_mfma_f32_16x16x32_bf16 v[120:123], v[80:83], v[196:199], v[120:123]
	v_mfma_f32_16x16x32_bf16 v[104:107], v[80:83], v[204:207], v[104:107]
	v_mfma_f32_16x16x32_bf16 v[88:91], v[80:83], v[212:215], v[88:91]
	v_mfma_f32_16x16x32_bf16 v[140:143], v[76:79], v[192:195], v[140:143]
	v_mfma_f32_16x16x32_bf16 v[124:127], v[76:79], v[200:203], v[124:127]
	v_mfma_f32_16x16x32_bf16 v[108:111], v[76:79], v[208:211], v[108:111]
	v_mfma_f32_16x16x32_bf16 v[92:95], v[76:79], v[230:233], v[92:95]
	v_mfma_f32_16x16x32_bf16 v[136:139], v[84:87], v[192:195], v[136:139]
	v_mfma_f32_16x16x32_bf16 v[120:123], v[84:87], v[200:203], v[120:123]
	v_mfma_f32_16x16x32_bf16 v[104:107], v[84:87], v[208:211], v[104:107]
	v_mfma_f32_16x16x32_bf16 v[88:91], v[84:87], v[230:233], v[88:91]
	s_setprio 0
	s_setprio 1
	v_mfma_f32_16x16x32_bf16 v[132:135], v[154:157], v[174:177], v[132:135]
	v_mfma_f32_16x16x32_bf16 v[116:119], v[154:157], v[196:199], v[116:119]
	v_mfma_f32_16x16x32_bf16 v[100:103], v[154:157], v[204:207], v[100:103]
	v_mfma_f32_16x16x32_bf16 v[68:71], v[154:157], v[212:215], v[68:71]
	v_mfma_f32_16x16x32_bf16 v[128:131], v[162:165], v[174:177], v[128:131]
	v_mfma_f32_16x16x32_bf16 v[112:115], v[162:165], v[196:199], v[112:115]
	v_mfma_f32_16x16x32_bf16 v[96:99], v[162:165], v[204:207], v[96:99]
	v_mfma_f32_16x16x32_bf16 v[64:67], v[162:165], v[212:215], v[64:67]
	v_mfma_f32_16x16x32_bf16 v[132:135], v[158:161], v[192:195], v[132:135]
	v_mfma_f32_16x16x32_bf16 v[116:119], v[158:161], v[200:203], v[116:119]
	v_mfma_f32_16x16x32_bf16 v[100:103], v[158:161], v[208:211], v[100:103]
	v_mfma_f32_16x16x32_bf16 v[68:71], v[158:161], v[230:233], v[68:71]
	v_mfma_f32_16x16x32_bf16 v[128:131], v[170:173], v[192:195], v[128:131]
	v_mfma_f32_16x16x32_bf16 v[112:115], v[170:173], v[200:203], v[112:115]
	v_mfma_f32_16x16x32_bf16 v[96:99], v[170:173], v[208:211], v[96:99]
	v_mfma_f32_16x16x32_bf16 v[64:67], v[170:173], v[230:233], v[64:67]
	s_setprio 0
	s_barrier
	s_add_i32 s41, s41, s23
	v_lshl_add_u64 v[178:179], s[16:17], 0, v[184:185]
	s_mov_b32 m0, s41
	ds_read_b128 v[174:177], v169 offset:16384
	ds_read_b128 v[192:195], v169 offset:17408
	ds_read_b128 v[196:199], v169 offset:18432
	ds_read_b128 v[200:203], v169 offset:19456
	ds_read_b128 v[204:207], v169 offset:20480
	ds_read_b128 v[208:211], v169 offset:21504
	ds_read_b128 v[212:215], v169 offset:22528
	ds_read_b128 v[230:233], v169 offset:23552
	global_load_lds_dwordx4 v[178:179], off
	s_add_i32 m0, s41, 0x2000
	s_add_u32 s42, s16, 0x40000
	v_lshl_add_u64 v[216:217], s[16:17], 0, v[148:149]
	s_addc_u32 s43, s17, 0
	s_add_i32 s41, s51, s23
	global_load_lds_dwordx4 v[216:217], off
	v_lshl_add_u64 v[234:235], s[42:43], 0, v[184:185]
	s_mov_b32 m0, s41
	v_lshl_add_u64 v[236:237], s[18:19], 0, v[146:147]
	global_load_lds_dwordx4 v[234:235], off
	v_lshl_add_u64 v[234:235], s[42:43], 0, v[148:149]
	s_add_i32 m0, s41, 0x2000
	s_nop 0
	global_load_lds_dwordx4 v[234:235], off
	v_lshl_add_u64 v[234:235], s[18:19], 0, v[144:145]
	s_mov_b32 m0, s26
	s_nop 0
	global_load_lds_dwordx4 v[234:235], off
	s_mov_b32 m0, s27
	s_nop 0
	global_load_lds_dwordx4 v[236:237], off
	s_waitcnt vmcnt(8)
	s_waitcnt lgkmcnt(0)
	s_barrier
; #define PG8_STAGE(bufoff, gbase, voff) do { _Pragma("unroll") for (int _i = 0; _i < 2; ++_i) \
;         __builtin_amdgcn_global_load_lds((const unsigned*)((const char*)(gbase) + (voff)[_i]), (LAS unsigned*)(lds + (bufoff) + ldsw + _i * 8192), 16, 0, 0); } while (0)
; #define PG8_LDA(dst, b, h) do { _Pragma("unroll") for (int m = 0; m < 4; ++m) _Pragma("unroll") for (int k = 0; k < 2; ++k) dst[m][k] = *(const LAS bf16x8*)(lds + PG8_SA(b, h) + aoff + m * 2048 + k * 1024); } while (0)
; #define PG8_LDB(dst, b, h) do { _Pragma("unroll") for (int n = 0; n < 2; ++n) _Pragma("unroll") for (int k = 0; k < 2; ++k) dst[n][k] = *(const LAS bf16x8*)(lds + PG8_SB(b, h) + boff + n * 2048 + k * 1024); } while (0)
; #define PG8_MMA(ai, bj, At, Bt) do { __builtin_amdgcn_s_setprio(1); _Pragma("unroll") for (int m = 0; m < 4; ++m) _Pragma("unroll") for (int n = 0; n < 2; ++n) _Pragma("unroll") for (int k = 0; k < 2; ++k) \
;         acc[ai][bj][m][n] = __builtin_amdgcn_mfma_f32_16x16x32_bf16(Bt[n][k], At[m][k], acc[ai][bj][m][n], 0, 0, 0); __builtin_amdgcn_s_setprio(0); } while (0)
; #define PG8_WAIT_V(n) asm volatile("s_waitcnt vmcnt(" #n ")" ::: "memory")
; #define PG8_WAIT_L(n) asm volatile("s_waitcnt lgkmcnt(" #n ")" ::: "memory")
; #define PG8_BAR __builtin_amdgcn_s_barrier()
; #define PG8_SCHED __builtin_amdgcn_sched_barrier(0)
; template <class Epi, class Sched>
; __device__ __forceinline__ void gemm_phase(LAS unsigned char* lds, const Gemm g, const Sched& S, const Epi& E) {
;     ...
;             PG8_WAIT_V(8); PG8_WAIT_L(0); PG8_BAR; PG8_MMA(1, 0, At, B0); PG8_MMA(1, 1, At, B1); PG8_BAR; PG8_SCHED;
;             PG8_LDB(B0, 1, 0); PG8_LDB(B1, 1, 1); PG8_SCHED; PG8_LDA(At, 1, 0); PG8_STAGE(PG8_SA(0, 1), a2 + hstep, voffA);
;             PG8_WAIT_V(8); PG8_WAIT_L(0); PG8_BAR; PG8_MMA(0, 0, At, B0); PG8_MMA(0, 1, At, B1); PG8_BAR; PG8_SCHED;
;             PG8_LDA(At, 1, 1); PG8_STAGE(PG8_SB(1, 0), b3, voffB); PG8_STAGE(PG8_SB(1, 1), b3 + hstep, voffB); PG8_STAGE(PG8_SA(1, 0), a3, voffA);
	s_setprio 1
	s_waitcnt lgkmcnt(0)
	v_mfma_f32_16x16x32_bf16 v[60:63], v[72:75], v[174:177], v[60:63]
	v_mfma_f32_16x16x32_bf16 v[44:47], v[72:75], v[196:199], v[44:47]
	v_mfma_f32_16x16x32_bf16 v[28:31], v[72:75], v[204:207], v[28:31]
	v_mfma_f32_16x16x32_bf16 v[12:15], v[72:75], v[212:215], v[12:15]
	v_mfma_f32_16x16x32_bf16 v[56:59], v[80:83], v[174:177], v[56:59]
	v_mfma_f32_16x16x32_bf16 v[40:43], v[80:83], v[196:199], v[40:43]
	v_mfma_f32_16x16x32_bf16 v[24:27], v[80:83], v[204:207], v[24:27]
	v_mfma_f32_16x16x32_bf16 v[8:11], v[80:83], v[212:215], v[8:11]
	v_mfma_f32_16x16x32_bf16 v[60:63], v[76:79], v[192:195], v[60:63]
	v_mfma_f32_16x16x32_bf16 v[44:47], v[76:79], v[200:203], v[44:47]
	v_mfma_f32_16x16x32_bf16 v[28:31], v[76:79], v[208:211], v[28:31]
	v_mfma_f32_16x16x32_bf16 v[12:15], v[76:79], v[230:233], v[12:15]
	v_mfma_f32_16x16x32_bf16 v[56:59], v[84:87], v[192:195], v[56:59]
	v_mfma_f32_16x16x32_bf16 v[40:43], v[84:87], v[200:203], v[40:43]
	v_mfma_f32_16x16x32_bf16 v[24:27], v[84:87], v[208:211], v[24:27]
	v_mfma_f32_16x16x32_bf16 v[8:11], v[84:87], v[230:233], v[8:11]
	s_setprio 0
	s_setprio 1
	v_mfma_f32_16x16x32_bf16 v[52:55], v[154:157], v[174:177], v[52:55]
	v_mfma_f32_16x16x32_bf16 v[36:39], v[154:157], v[196:199], v[36:39]
	v_mfma_f32_16x16x32_bf16 v[20:23], v[154:157], v[204:207], v[20:23]
	v_mfma_f32_16x16x32_bf16 v[4:7], v[154:157], v[212:215], v[4:7]
	v_mfma_f32_16x16x32_bf16 v[48:51], v[162:165], v[174:177], v[48:51]
	v_mfma_f32_16x16x32_bf16 v[32:35], v[162:165], v[196:199], v[32:35]
	v_mfma_f32_16x16x32_bf16 v[16:19], v[162:165], v[204:207], v[16:19]
	v_mfma_f32_16x16x32_bf16 v[0:3], v[162:165], v[212:215], v[0:3]
	v_mfma_f32_16x16x32_bf16 v[52:55], v[158:161], v[192:195], v[52:55]
	v_mfma_f32_16x16x32_bf16 v[36:39], v[158:161], v[200:203], v[36:39]
	v_mfma_f32_16x16x32_bf16 v[20:23], v[158:161], v[208:211], v[20:23]
	v_mfma_f32_16x16x32_bf16 v[4:7], v[158:161], v[230:233], v[4:7]
	v_mfma_f32_16x16x32_bf16 v[48:51], v[170:173], v[192:195], v[48:51]
	v_mfma_f32_16x16x32_bf16 v[32:35], v[170:173], v[200:203], v[32:35]
	v_mfma_f32_16x16x32_bf16 v[16:19], v[170:173], v[208:211], v[16:19]
	v_mfma_f32_16x16x32_bf16 v[0:3], v[170:173], v[230:233], v[0:3]
	s_setprio 0
	s_barrier
	s_add_i32 s41, 0, 0x18000
	s_add_i32 s42, 0, 0x1c000
	v_add_u32_e32 v84, s41, v168
	v_add_u32_e32 v170, s42, v168
	ds_read_b128 v[72:75], v84
	ds_read_b128 v[76:79], v84 offset:1024
	ds_read_b128 v[80:83], v84 offset:2048
	ds_read_b128 v[84:87], v84 offset:3072
	ds_read_b128 v[154:157], v170
	ds_read_b128 v[158:161], v170 offset:1024
	ds_read_b128 v[162:165], v170 offset:2048
	ds_read_b128 v[170:173], v170 offset:3072
	s_add_u32 s18, s18, 0x40000
	s_addc_u32 s19, s19, 0
	s_mov_b32 m0, s28
	v_lshl_add_u64 v[238:239], s[18:19], 0, v[144:145]
	ds_read_b128 v[174:177], v169 offset:32768
	ds_read_b128 v[192:195], v169 offset:33792
	ds_read_b128 v[196:199], v169 offset:34816
	ds_read_b128 v[200:203], v169 offset:35840
	ds_read_b128 v[204:207], v169 offset:36864
	ds_read_b128 v[208:211], v169 offset:37888
	ds_read_b128 v[212:215], v169 offset:38912
	ds_read_b128 v[230:233], v169 offset:39936
	global_load_lds_dwordx4 v[238:239], off
	v_lshl_add_u64 v[238:239], s[18:19], 0, v[146:147]
	s_mov_b32 m0, s29
	s_nop 0
	global_load_lds_dwordx4 v[238:239], off
	s_waitcnt vmcnt(8)
	s_waitcnt lgkmcnt(0)
	s_barrier
	s_setprio 1
	s_waitcnt lgkmcnt(0)
	v_mfma_f32_16x16x32_bf16 v[140:143], v[72:75], v[174:177], v[140:143]
	v_mfma_f32_16x16x32_bf16 v[124:127], v[72:75], v[196:199], v[124:127]
	v_mfma_f32_16x16x32_bf16 v[108:111], v[72:75], v[204:207], v[108:111]
	v_mfma_f32_16x16x32_bf16 v[92:95], v[72:75], v[212:215], v[92:95]
	v_mfma_f32_16x16x32_bf16 v[136:139], v[80:83], v[174:177], v[136:139]
	v_mfma_f32_16x16x32_bf16 v[120:123], v[80:83], v[196:199], v[120:123]
	v_mfma_f32_16x16x32_bf16 v[104:107], v[80:83], v[204:207], v[104:107]
	v_mfma_f32_16x16x32_bf16 v[88:91], v[80:83], v[212:215], v[88:91]
	v_mfma_f32_16x16x32_bf16 v[140:143], v[76:79], v[192:195], v[140:143]
	v_mfma_f32_16x16x32_bf16 v[124:127], v[76:79], v[200:203], v[124:127]
	v_mfma_f32_16x16x32_bf16 v[108:111], v[76:79], v[208:211], v[108:111]
	v_mfma_f32_16x16x32_bf16 v[92:95], v[76:79], v[230:233], v[92:95]
	v_mfma_f32_16x16x32_bf16 v[136:139], v[84:87], v[192:195], v[136:139]
	v_mfma_f32_16x16x32_bf16 v[120:123], v[84:87], v[200:203], v[120:123]
	v_mfma_f32_16x16x32_bf16 v[104:107], v[84:87], v[208:211], v[104:107]
	v_mfma_f32_16x16x32_bf16 v[88:91], v[84:87], v[230:233], v[88:91]
	s_setprio 0
	s_setprio 1
	v_mfma_f32_16x16x32_bf16 v[132:135], v[154:157], v[174:177], v[132:135]
	v_mfma_f32_16x16x32_bf16 v[116:119], v[154:157], v[196:199], v[116:119]
	v_mfma_f32_16x16x32_bf16 v[100:103], v[154:157], v[204:207], v[100:103]
	v_mfma_f32_16x16x32_bf16 v[68:71], v[154:157], v[212:215], v[68:71]
	v_mfma_f32_16x16x32_bf16 v[128:131], v[162:165], v[174:177], v[128:131]
	v_mfma_f32_16x16x32_bf16 v[112:115], v[162:165], v[196:199], v[112:115]
	v_mfma_f32_16x16x32_bf16 v[96:99], v[162:165], v[204:207], v[96:99]
	v_mfma_f32_16x16x32_bf16 v[64:67], v[162:165], v[212:215], v[64:67]
	v_mfma_f32_16x16x32_bf16 v[132:135], v[158:161], v[192:195], v[132:135]
	v_mfma_f32_16x16x32_bf16 v[116:119], v[158:161], v[200:203], v[116:119]
	v_mfma_f32_16x16x32_bf16 v[100:103], v[158:161], v[208:211], v[100:103]
	v_mfma_f32_16x16x32_bf16 v[68:71], v[158:161], v[230:233], v[68:71]
	v_mfma_f32_16x16x32_bf16 v[128:131], v[170:173], v[192:195], v[128:131]
	v_mfma_f32_16x16x32_bf16 v[112:115], v[170:173], v[200:203], v[112:115]
	v_mfma_f32_16x16x32_bf16 v[96:99], v[170:173], v[208:211], v[96:99]
	v_mfma_f32_16x16x32_bf16 v[64:67], v[170:173], v[230:233], v[64:67]
	s_setprio 0
	s_barrier
; #define PG8_STAGE(bufoff, gbase, voff) do { _Pragma("unroll") for (int _i = 0; _i < 2; ++_i) \
;         __builtin_amdgcn_global_load_lds((const unsigned*)((const char*)(gbase) + (voff)[_i]), (LAS unsigned*)(lds + (bufoff) + ldsw + _i * 8192), 16, 0, 0); } while (0)
; #define PG8_LDA(dst, b, h) do { _Pragma("unroll") for (int m = 0; m < 4; ++m) _Pragma("unroll") for (int k = 0; k < 2; ++k) dst[m][k] = *(const LAS bf16x8*)(lds + PG8_SA(b, h) + aoff + m * 2048 + k * 1024); } while (0)
; #define PG8_MMA(ai, bj, At, Bt) do { __builtin_amdgcn_s_setprio(1); _Pragma("unroll") for (int m = 0; m < 4; ++m) _Pragma("unroll") for (int n = 0; n < 2; ++n) _Pragma("unroll") for (int k = 0; k < 2; ++k) \
;         acc[ai][bj][m][n] = __builtin_amdgcn_mfma_f32_16x16x32_bf16(Bt[n][k], At[m][k], acc[ai][bj][m][n], 0, 0, 0); __builtin_amdgcn_s_setprio(0); } while (0)
; #define PG8_WAIT_V(n) asm volatile("s_waitcnt vmcnt(" #n ")" ::: "memory")
; #define PG8_WAIT_L(n) asm volatile("s_waitcnt lgkmcnt(" #n ")" ::: "memory")
; #define PG8_BAR __builtin_amdgcn_s_barrier()
; #define PG8_SCHED __builtin_amdgcn_sched_barrier(0)
; template <class Epi, class Sched>
; __device__ __forceinline__ void gemm_phase(LAS unsigned char* lds, const Gemm g, const Sched& S, const Epi& E) {
;     ...
;         for (int t = 0; t < nt; t += 2) {
;             const bool last = (t == nt - 2);
;     ...
;             PG8_LDA(At, 1, 1); PG8_STAGE(PG8_SB(1, 0), b3, voffB); PG8_STAGE(PG8_SB(1, 1), b3 + hstep, voffB); PG8_STAGE(PG8_SA(1, 0), a3, voffA);
;             PG8_WAIT_V(8); PG8_WAIT_L(0); PG8_BAR; PG8_MMA(1, 0, At, B0); PG8_MMA(1, 1, At, B1); PG8_BAR; PG8_SCHED;
;         }
	s_add_i32 s18, s41, s23
	v_lshl_add_u64 v[178:179], v[178:179], 0, s[84:85]
	s_mov_b32 m0, s18
	ds_read_b128 v[174:177], v169 offset:49152
	ds_read_b128 v[192:195], v169 offset:50176
	ds_read_b128 v[196:199], v169 offset:51200
	ds_read_b128 v[200:203], v169 offset:52224
	ds_read_b128 v[204:207], v169 offset:53248
	ds_read_b128 v[208:211], v169 offset:54272
	ds_read_b128 v[212:215], v169 offset:55296
	ds_read_b128 v[230:233], v169 offset:56320
	global_load_lds_dwordx4 v[178:179], off
	s_add_i32 m0, s18, 0x2000
	s_add_u32 s16, s16, 0x40080
	v_lshl_add_u64 v[178:179], v[216:217], 0, s[84:85]
	s_addc_u32 s17, s17, 0
	s_add_i32 s18, s42, s23
	global_load_lds_dwordx4 v[178:179], off
	v_lshl_add_u64 v[178:179], s[16:17], 0, v[184:185]
	s_mov_b32 m0, s18
	s_nop 0
	global_load_lds_dwordx4 v[178:179], off
	v_lshl_add_u64 v[178:179], s[16:17], 0, v[148:149]
	s_add_i32 m0, s18, 0x2000
	s_nop 0
	global_load_lds_dwordx4 v[178:179], off
	v_lshl_add_u64 v[178:179], v[234:235], 0, s[84:85]
	s_mov_b32 m0, s34
	s_nop 0
	global_load_lds_dwordx4 v[178:179], off
	v_lshl_add_u64 v[178:179], v[236:237], 0, s[84:85]
	s_mov_b32 m0, s35
	s_nop 0
	global_load_lds_dwordx4 v[178:179], off
	s_waitcnt vmcnt(8)
	s_waitcnt lgkmcnt(0)
	s_barrier
	s_setprio 1
	s_waitcnt lgkmcnt(0)
	v_mfma_f32_16x16x32_bf16 v[60:63], v[72:75], v[174:177], v[60:63]
	v_mfma_f32_16x16x32_bf16 v[44:47], v[72:75], v[196:199], v[44:47]
	v_mfma_f32_16x16x32_bf16 v[28:31], v[72:75], v[204:207], v[28:31]
	v_mfma_f32_16x16x32_bf16 v[12:15], v[72:75], v[212:215], v[12:15]
	v_mfma_f32_16x16x32_bf16 v[56:59], v[80:83], v[174:177], v[56:59]
	v_mfma_f32_16x16x32_bf16 v[40:43], v[80:83], v[196:199], v[40:43]
	v_mfma_f32_16x16x32_bf16 v[24:27], v[80:83], v[204:207], v[24:27]
	v_mfma_f32_16x16x32_bf16 v[8:11], v[80:83], v[212:215], v[8:11]
	v_mfma_f32_16x16x32_bf16 v[60:63], v[76:79], v[192:195], v[60:63]
	v_mfma_f32_16x16x32_bf16 v[44:47], v[76:79], v[200:203], v[44:47]
	v_mfma_f32_16x16x32_bf16 v[28:31], v[76:79], v[208:211], v[28:31]
	v_mfma_f32_16x16x32_bf16 v[12:15], v[76:79], v[230:233], v[12:15]
	v_mfma_f32_16x16x32_bf16 v[56:59], v[84:87], v[192:195], v[56:59]
	v_mfma_f32_16x16x32_bf16 v[40:43], v[84:87], v[200:203], v[40:43]
	v_mfma_f32_16x16x32_bf16 v[24:27], v[84:87], v[208:211], v[24:27]
	v_mfma_f32_16x16x32_bf16 v[8:11], v[84:87], v[230:233], v[8:11]
	s_setprio 0
	s_setprio 1
	v_mfma_f32_16x16x32_bf16 v[52:55], v[154:157], v[174:177], v[52:55]
	v_mfma_f32_16x16x32_bf16 v[36:39], v[154:157], v[196:199], v[36:39]
	v_mfma_f32_16x16x32_bf16 v[20:23], v[154:157], v[204:207], v[20:23]
	v_mfma_f32_16x16x32_bf16 v[4:7], v[154:157], v[212:215], v[4:7]
	v_mfma_f32_16x16x32_bf16 v[48:51], v[162:165], v[174:177], v[48:51]
	v_mfma_f32_16x16x32_bf16 v[32:35], v[162:165], v[196:199], v[32:35]
	v_mfma_f32_16x16x32_bf16 v[16:19], v[162:165], v[204:207], v[16:19]
	v_mfma_f32_16x16x32_bf16 v[0:3], v[162:165], v[212:215], v[0:3]
	v_mfma_f32_16x16x32_bf16 v[52:55], v[158:161], v[192:195], v[52:55]
	v_mfma_f32_16x16x32_bf16 v[36:39], v[158:161], v[200:203], v[36:39]
	v_mfma_f32_16x16x32_bf16 v[20:23], v[158:161], v[208:211], v[20:23]
	v_mfma_f32_16x16x32_bf16 v[4:7], v[158:161], v[230:233], v[4:7]
	v_mfma_f32_16x16x32_bf16 v[48:51], v[170:173], v[192:195], v[48:51]
	v_mfma_f32_16x16x32_bf16 v[32:35], v[170:173], v[200:203], v[32:35]
	v_mfma_f32_16x16x32_bf16 v[16:19], v[170:173], v[208:211], v[16:19]
	v_mfma_f32_16x16x32_bf16 v[0:3], v[170:173], v[230:233], v[0:3]
	s_setprio 0
	s_barrier
	s_add_i32 s40, s40, 2
	s_add_u32 s14, s14, 0x100
	s_addc_u32 s15, s15, 0
	s_add_u32 s21, s21, 0x100
	s_addc_u32 s33, s33, 0
	s_cmp_gt_u32 s40, 13
	s_cbranch_scc0 .LBB0_503
	s_and_b64 vcc, exec, s[48:49]
	s_cbranch_vccz .LBB0_506
	s_barrier

; #define PG8_STAGE(bufoff, gbase, voff) do { _Pragma("unroll") for (int _i = 0; _i < 2; ++_i) \
;         __builtin_amdgcn_global_load_lds((const unsigned*)((const char*)(gbase) + (voff)[_i]), (LAS unsigned*)(lds + (bufoff) + ldsw + _i * 8192), 16, 0, 0); } while (0)
; #define PG8_LDA(dst, b, h) do { _Pragma("unroll") for (int m = 0; m < 4; ++m) _Pragma("unroll") for (int k = 0; k < 2; ++k) dst[m][k] = *(const LAS bf16x8*)(lds + PG8_SA(b, h) + aoff + m * 2048 + k * 1024); } while (0)
; #define PG8_LDB(dst, b, h) do { _Pragma("unroll") for (int n = 0; n < 2; ++n) _Pragma("unroll") for (int k = 0; k < 2; ++k) dst[n][k] = *(const LAS bf16x8*)(lds + PG8_SB(b, h) + boff + n * 2048 + k * 1024); } while (0)
; #define PG8_MMA(ai, bj, At, Bt) do { __builtin_amdgcn_s_setprio(1); _Pragma("unroll") for (int m = 0; m < 4; ++m) _Pragma("unroll") for (int n = 0; n < 2; ++n) _Pragma("unroll") for (int k = 0; k < 2; ++k) \
;         acc[ai][bj][m][n] = __builtin_amdgcn_mfma_f32_16x16x32_bf16(Bt[n][k], At[m][k], acc[ai][bj][m][n], 0, 0, 0); __builtin_amdgcn_s_setprio(0); } while (0)
; #define PG8_WAIT_V(n) asm volatile("s_waitcnt vmcnt(" #n ")" ::: "memory")
; #define PG8_WAIT_L(n) asm volatile("s_waitcnt lgkmcnt(" #n ")" ::: "memory")
; #define PG8_BAR __builtin_amdgcn_s_barrier()
; #define PG8_SCHED __builtin_amdgcn_sched_barrier(0)
; template <class Epi, class Sched>
; __device__ __forceinline__ void gemm_phase(LAS unsigned char* lds, const Gemm g, const Sched& S, const Epi& E) {
;     ...
;         for (int t = 0; t < nt; t += 2) {
;             const bool last = (t == nt - 2);
;             const char* a1 = cA + (size_t)(t + 1) * kstep;
;             const char* a2 = last ? nA : cA + (size_t)(t + 2) * kstep; const char* b2 = last ? nB : cB + (size_t)(t + 2) * kstep;
;             const char* a3 = a2 + kstep; const char* b3 = b2 + kstep;
;             PG8_LDB(B0, 0, 0); PG8_LDB(B1, 0, 1); PG8_SCHED; PG8_LDA(At, 0, 0); PG8_STAGE(PG8_SA(1, 1), a1 + hstep, voffA);
;             PG8_WAIT_V(8); PG8_WAIT_L(0); PG8_BAR; PG8_MMA(0, 0, At, B0); PG8_MMA(0, 1, At, B1); PG8_BAR; PG8_SCHED;
;             PG8_LDA(At, 0, 1); PG8_STAGE(PG8_SB(0, 0), b2, voffB); PG8_STAGE(PG8_SB(0, 1), b2 + hstep, voffB); PG8_STAGE(PG8_SA(0, 0), a2, voffA);
.LBB0_599:
	s_add_i32 s19, s17, 2
	s_add_u32 s14, s6, 0x80
	s_addc_u32 s15, s7, 0
	s_add_i32 s33, 0, 0x10000
	s_cmp_eq_u32 s12, s17
	s_cselect_b32 s15, s1, s15
	s_cselect_b32 s14, s0, s14
	s_cselect_b32 s43, s65, s16
	s_cselect_b32 s42, s64, s13
	s_add_i32 s17, 0, 0x14000
	v_add_u32_e32 v140, s33, v231
	v_add_u32_e32 v156, s17, v231
	s_waitcnt lgkmcnt(0)
	ds_read_b128 v[128:131], v140
	ds_read_b128 v[132:135], v140 offset:1024
	ds_read_b128 v[136:139], v140 offset:2048
	ds_read_b128 v[140:143], v140 offset:3072
	ds_read_b128 v[144:147], v156
	ds_read_b128 v[148:151], v156 offset:1024
	ds_read_b128 v[152:155], v156 offset:2048
	ds_read_b128 v[156:159], v156 offset:3072
	v_lshl_add_u64 v[214:215], s[6:7], 0, v[198:199]
	s_add_i32 m0, s29, 0xc000
	ds_read_b128 v[160:163], v232
	ds_read_b128 v[164:167], v232 offset:1024
	ds_read_b128 v[168:171], v232 offset:2048
	ds_read_b128 v[172:175], v232 offset:3072
	ds_read_b128 v[176:179], v232 offset:4096
	ds_read_b128 v[202:205], v232 offset:5120
	ds_read_b128 v[206:209], v232 offset:6144
	ds_read_b128 v[210:213], v232 offset:7168
	global_load_lds_dwordx4 v[214:215], off
	v_lshl_add_u64 v[214:215], s[6:7], 0, v[200:201]
	s_add_i32 m0, s29, 0xe000
	s_nop 0
	global_load_lds_dwordx4 v[214:215], off
	s_waitcnt vmcnt(8)
	s_waitcnt lgkmcnt(0)
	s_barrier
	s_setprio 1
	s_waitcnt lgkmcnt(0)
	v_mfma_f32_16x16x32_bf16 v[124:127], v[128:131], v[160:163], v[124:127]
	v_mfma_f32_16x16x32_bf16 v[116:119], v[128:131], v[168:171], v[116:119]
	v_mfma_f32_16x16x32_bf16 v[104:107], v[128:131], v[176:179], v[104:107]
	v_mfma_f32_16x16x32_bf16 v[88:91], v[128:131], v[206:209], v[88:91]
	v_mfma_f32_16x16x32_bf16 v[120:123], v[136:139], v[160:163], v[120:123]
	v_mfma_f32_16x16x32_bf16 v[112:115], v[136:139], v[168:171], v[112:115]
	v_mfma_f32_16x16x32_bf16 v[96:99], v[136:139], v[176:179], v[96:99]
	v_mfma_f32_16x16x32_bf16 v[80:83], v[136:139], v[206:209], v[80:83]
	v_mfma_f32_16x16x32_bf16 v[124:127], v[132:135], v[164:167], v[124:127]
	v_mfma_f32_16x16x32_bf16 v[116:119], v[132:135], v[172:175], v[116:119]
	v_mfma_f32_16x16x32_bf16 v[104:107], v[132:135], v[202:205], v[104:107]
	v_mfma_f32_16x16x32_bf16 v[88:91], v[132:135], v[210:213], v[88:91]
	v_mfma_f32_16x16x32_bf16 v[120:123], v[140:143], v[164:167], v[120:123]
	v_mfma_f32_16x16x32_bf16 v[112:115], v[140:143], v[172:175], v[112:115]
	v_mfma_f32_16x16x32_bf16 v[96:99], v[140:143], v[202:205], v[96:99]
	v_mfma_f32_16x16x32_bf16 v[80:83], v[140:143], v[210:213], v[80:83]
	s_setprio 0
	s_setprio 1
	v_mfma_f32_16x16x32_bf16 v[108:111], v[144:147], v[160:163], v[108:111]
	v_mfma_f32_16x16x32_bf16 v[92:95], v[144:147], v[168:171], v[92:95]
	v_mfma_f32_16x16x32_bf16 v[76:79], v[144:147], v[176:179], v[76:79]
	v_mfma_f32_16x16x32_bf16 v[68:71], v[144:147], v[206:209], v[68:71]
	v_mfma_f32_16x16x32_bf16 v[100:103], v[152:155], v[160:163], v[100:103]
	v_mfma_f32_16x16x32_bf16 v[84:87], v[152:155], v[168:171], v[84:87]
	v_mfma_f32_16x16x32_bf16 v[72:75], v[152:155], v[176:179], v[72:75]
	v_mfma_f32_16x16x32_bf16 v[64:67], v[152:155], v[206:209], v[64:67]
	v_mfma_f32_16x16x32_bf16 v[108:111], v[148:151], v[164:167], v[108:111]
	v_mfma_f32_16x16x32_bf16 v[92:95], v[148:151], v[172:175], v[92:95]
	v_mfma_f32_16x16x32_bf16 v[76:79], v[148:151], v[202:205], v[76:79]
	v_mfma_f32_16x16x32_bf16 v[68:71], v[148:151], v[210:213], v[68:71]
	v_mfma_f32_16x16x32_bf16 v[100:103], v[156:159], v[164:167], v[100:103]
	v_mfma_f32_16x16x32_bf16 v[84:87], v[156:159], v[172:175], v[84:87]
	v_mfma_f32_16x16x32_bf16 v[72:75], v[156:159], v[202:205], v[72:75]
	v_mfma_f32_16x16x32_bf16 v[64:67], v[156:159], v[210:213], v[64:67]
	s_setprio 0
	s_barrier
	s_add_i32 s33, s33, s28
	v_lshl_add_u64 v[214:215], s[42:43], 0, v[184:185]
	s_mov_b32 m0, s33
	ds_read_b128 v[160:163], v232 offset:16384
	ds_read_b128 v[164:167], v232 offset:17408
	ds_read_b128 v[168:171], v232 offset:18432
	ds_read_b128 v[172:175], v232 offset:19456
	ds_read_b128 v[176:179], v232 offset:20480
	ds_read_b128 v[202:205], v232 offset:21504
	ds_read_b128 v[206:209], v232 offset:22528
	ds_read_b128 v[210:213], v232 offset:23552
	global_load_lds_dwordx4 v[214:215], off
	s_add_i32 m0, s33, 0x2000
	v_lshl_add_u64 v[216:217], s[42:43], 0, v[196:197]
	s_add_u32 s42, s42, s54
	s_addc_u32 s43, s43, 0
	s_add_i32 s17, s17, s28
	global_load_lds_dwordx4 v[216:217], off
	v_lshl_add_u64 v[234:235], s[42:43], 0, v[184:185]
	s_mov_b32 m0, s17
	v_lshl_add_u64 v[236:237], s[42:43], 0, v[196:197]
	global_load_lds_dwordx4 v[234:235], off
	s_add_i32 m0, s17, 0x2000
	v_lshl_add_u64 v[238:239], s[14:15], 0, v[192:193]
	global_load_lds_dwordx4 v[236:237], off
	s_mov_b32 m0, s29
	v_lshl_add_u64 v[240:241], s[14:15], 0, v[194:195]
	global_load_lds_dwordx4 v[238:239], off
	s_mov_b32 m0, s30
	s_nop 0
	global_load_lds_dwordx4 v[240:241], off
	s_waitcnt vmcnt(8)
	s_waitcnt lgkmcnt(0)
	s_barrier
; #define PG8_STAGE(bufoff, gbase, voff) do { _Pragma("unroll") for (int _i = 0; _i < 2; ++_i) \
;         __builtin_amdgcn_global_load_lds((const unsigned*)((const char*)(gbase) + (voff)[_i]), (LAS unsigned*)(lds + (bufoff) + ldsw + _i * 8192), 16, 0, 0); } while (0)
; #define PG8_LDA(dst, b, h) do { _Pragma("unroll") for (int m = 0; m < 4; ++m) _Pragma("unroll") for (int k = 0; k < 2; ++k) dst[m][k] = *(const LAS bf16x8*)(lds + PG8_SA(b, h) + aoff + m * 2048 + k * 1024); } while (0)
; #define PG8_LDB(dst, b, h) do { _Pragma("unroll") for (int n = 0; n < 2; ++n) _Pragma("unroll") for (int k = 0; k < 2; ++k) dst[n][k] = *(const LAS bf16x8*)(lds + PG8_SB(b, h) + boff + n * 2048 + k * 1024); } while (0)
; #define PG8_MMA(ai, bj, At, Bt) do { __builtin_amdgcn_s_setprio(1); _Pragma("unroll") for (int m = 0; m < 4; ++m) _Pragma("unroll") for (int n = 0; n < 2; ++n) _Pragma("unroll") for (int k = 0; k < 2; ++k) \
;         acc[ai][bj][m][n] = __builtin_amdgcn_mfma_f32_16x16x32_bf16(Bt[n][k], At[m][k], acc[ai][bj][m][n], 0, 0, 0); __builtin_amdgcn_s_setprio(0); } while (0)
; #define PG8_WAIT_V(n) asm volatile("s_waitcnt vmcnt(" #n ")" ::: "memory")
; #define PG8_WAIT_L(n) asm volatile("s_waitcnt lgkmcnt(" #n ")" ::: "memory")
; #define PG8_BAR __builtin_amdgcn_s_barrier()
; #define PG8_SCHED __builtin_amdgcn_sched_barrier(0)
; template <class Epi, class Sched>
; __device__ __forceinline__ void gemm_phase(LAS unsigned char* lds, const Gemm g, const Sched& S, const Epi& E) {
;     ...
;             PG8_WAIT_V(8); PG8_WAIT_L(0); PG8_BAR; PG8_MMA(1, 0, At, B0); PG8_MMA(1, 1, At, B1); PG8_BAR; PG8_SCHED;
;             PG8_LDB(B0, 1, 0); PG8_LDB(B1, 1, 1); PG8_SCHED; PG8_LDA(At, 1, 0); PG8_STAGE(PG8_SA(0, 1), a2 + hstep, voffA);
;             PG8_WAIT_V(8); PG8_WAIT_L(0); PG8_BAR; PG8_MMA(0, 0, At, B0); PG8_MMA(0, 1, At, B1); PG8_BAR; PG8_SCHED;
	s_setprio 1
	s_waitcnt lgkmcnt(0)
	v_mfma_f32_16x16x32_bf16 v[60:63], v[128:131], v[160:163], v[60:63]
	v_mfma_f32_16x16x32_bf16 v[52:55], v[128:131], v[168:171], v[52:55]
	v_mfma_f32_16x16x32_bf16 v[36:39], v[128:131], v[176:179], v[36:39]
	v_mfma_f32_16x16x32_bf16 v[20:23], v[128:131], v[206:209], v[20:23]
	v_mfma_f32_16x16x32_bf16 v[56:59], v[136:139], v[160:163], v[56:59]
	v_mfma_f32_16x16x32_bf16 v[48:51], v[136:139], v[168:171], v[48:51]
	v_mfma_f32_16x16x32_bf16 v[32:35], v[136:139], v[176:179], v[32:35]
	v_mfma_f32_16x16x32_bf16 v[16:19], v[136:139], v[206:209], v[16:19]
	v_mfma_f32_16x16x32_bf16 v[60:63], v[132:135], v[164:167], v[60:63]
	v_mfma_f32_16x16x32_bf16 v[52:55], v[132:135], v[172:175], v[52:55]
	v_mfma_f32_16x16x32_bf16 v[36:39], v[132:135], v[202:205], v[36:39]
	v_mfma_f32_16x16x32_bf16 v[20:23], v[132:135], v[210:213], v[20:23]
	v_mfma_f32_16x16x32_bf16 v[56:59], v[140:143], v[164:167], v[56:59]
	v_mfma_f32_16x16x32_bf16 v[48:51], v[140:143], v[172:175], v[48:51]
	v_mfma_f32_16x16x32_bf16 v[32:35], v[140:143], v[202:205], v[32:35]
	v_mfma_f32_16x16x32_bf16 v[16:19], v[140:143], v[210:213], v[16:19]
	s_setprio 0
	s_setprio 1
	v_mfma_f32_16x16x32_bf16 v[44:47], v[144:147], v[160:163], v[44:47]
	v_mfma_f32_16x16x32_bf16 v[28:31], v[144:147], v[168:171], v[28:31]
	v_mfma_f32_16x16x32_bf16 v[12:15], v[144:147], v[176:179], v[12:15]
	v_mfma_f32_16x16x32_bf16 v[4:7], v[144:147], v[206:209], v[4:7]
	v_mfma_f32_16x16x32_bf16 v[40:43], v[152:155], v[160:163], v[40:43]
	v_mfma_f32_16x16x32_bf16 v[24:27], v[152:155], v[168:171], v[24:27]
	v_mfma_f32_16x16x32_bf16 v[8:11], v[152:155], v[176:179], v[8:11]
	v_mfma_f32_16x16x32_bf16 v[0:3], v[152:155], v[206:209], v[0:3]
	v_mfma_f32_16x16x32_bf16 v[44:47], v[148:151], v[164:167], v[44:47]
	v_mfma_f32_16x16x32_bf16 v[28:31], v[148:151], v[172:175], v[28:31]
	v_mfma_f32_16x16x32_bf16 v[12:15], v[148:151], v[202:205], v[12:15]
	v_mfma_f32_16x16x32_bf16 v[4:7], v[148:151], v[210:213], v[4:7]
	v_mfma_f32_16x16x32_bf16 v[40:43], v[156:159], v[164:167], v[40:43]
	v_mfma_f32_16x16x32_bf16 v[24:27], v[156:159], v[172:175], v[24:27]
	v_mfma_f32_16x16x32_bf16 v[8:11], v[156:159], v[202:205], v[8:11]
	v_mfma_f32_16x16x32_bf16 v[0:3], v[156:159], v[210:213], v[0:3]
	s_setprio 0
	s_barrier
	s_add_i32 s17, 0, 0x18000
	s_add_i32 s33, 0, 0x1c000
	v_add_u32_e32 v140, s17, v231
	v_add_u32_e32 v156, s33, v231
	ds_read_b128 v[128:131], v140
	ds_read_b128 v[132:135], v140 offset:1024
	ds_read_b128 v[136:139], v140 offset:2048
	ds_read_b128 v[140:143], v140 offset:3072
	ds_read_b128 v[144:147], v156
	ds_read_b128 v[148:151], v156 offset:1024
	ds_read_b128 v[152:155], v156 offset:2048
	ds_read_b128 v[156:159], v156 offset:3072
	s_add_u32 s14, s14, s54
	s_addc_u32 s15, s15, 0
	s_mov_b32 m0, s31
	v_lshl_add_u64 v[242:243], s[14:15], 0, v[192:193]
	ds_read_b128 v[160:163], v232 offset:32768
	ds_read_b128 v[164:167], v232 offset:33792
	ds_read_b128 v[168:171], v232 offset:34816
	ds_read_b128 v[172:175], v232 offset:35840
	ds_read_b128 v[176:179], v232 offset:36864
	ds_read_b128 v[202:205], v232 offset:37888
	ds_read_b128 v[206:209], v232 offset:38912
	ds_read_b128 v[210:213], v232 offset:39936
	global_load_lds_dwordx4 v[242:243], off
	v_lshl_add_u64 v[242:243], s[14:15], 0, v[194:195]
	s_mov_b32 m0, s34
	s_nop 0
	global_load_lds_dwordx4 v[242:243], off
	s_waitcnt vmcnt(8)
	s_waitcnt lgkmcnt(0)
	s_barrier
	s_setprio 1
	s_waitcnt lgkmcnt(0)
	v_mfma_f32_16x16x32_bf16 v[124:127], v[128:131], v[160:163], v[124:127]
	v_mfma_f32_16x16x32_bf16 v[116:119], v[128:131], v[168:171], v[116:119]
	v_mfma_f32_16x16x32_bf16 v[104:107], v[128:131], v[176:179], v[104:107]
	v_mfma_f32_16x16x32_bf16 v[88:91], v[128:131], v[206:209], v[88:91]
	v_mfma_f32_16x16x32_bf16 v[120:123], v[136:139], v[160:163], v[120:123]
	v_mfma_f32_16x16x32_bf16 v[112:115], v[136:139], v[168:171], v[112:115]
	v_mfma_f32_16x16x32_bf16 v[96:99], v[136:139], v[176:179], v[96:99]
	v_mfma_f32_16x16x32_bf16 v[80:83], v[136:139], v[206:209], v[80:83]
	v_mfma_f32_16x16x32_bf16 v[124:127], v[132:135], v[164:167], v[124:127]
	v_mfma_f32_16x16x32_bf16 v[116:119], v[132:135], v[172:175], v[116:119]
	v_mfma_f32_16x16x32_bf16 v[104:107], v[132:135], v[202:205], v[104:107]
	v_mfma_f32_16x16x32_bf16 v[88:91], v[132:135], v[210:213], v[88:91]
	v_mfma_f32_16x16x32_bf16 v[120:123], v[140:143], v[164:167], v[120:123]
	v_mfma_f32_16x16x32_bf16 v[112:115], v[140:143], v[172:175], v[112:115]
	v_mfma_f32_16x16x32_bf16 v[96:99], v[140:143], v[202:205], v[96:99]
	v_mfma_f32_16x16x32_bf16 v[80:83], v[140:143], v[210:213], v[80:83]
	s_setprio 0
	s_setprio 1
	v_mfma_f32_16x16x32_bf16 v[108:111], v[144:147], v[160:163], v[108:111]
	v_mfma_f32_16x16x32_bf16 v[92:95], v[144:147], v[168:171], v[92:95]
	v_mfma_f32_16x16x32_bf16 v[76:79], v[144:147], v[176:179], v[76:79]
	v_mfma_f32_16x16x32_bf16 v[68:71], v[144:147], v[206:209], v[68:71]
	v_mfma_f32_16x16x32_bf16 v[100:103], v[152:155], v[160:163], v[100:103]
	v_mfma_f32_16x16x32_bf16 v[84:87], v[152:155], v[168:171], v[84:87]
	v_mfma_f32_16x16x32_bf16 v[72:75], v[152:155], v[176:179], v[72:75]
	v_mfma_f32_16x16x32_bf16 v[64:67], v[152:155], v[206:209], v[64:67]
	v_mfma_f32_16x16x32_bf16 v[108:111], v[148:151], v[164:167], v[108:111]
	v_mfma_f32_16x16x32_bf16 v[92:95], v[148:151], v[172:175], v[92:95]
	v_mfma_f32_16x16x32_bf16 v[76:79], v[148:151], v[202:205], v[76:79]
	v_mfma_f32_16x16x32_bf16 v[68:71], v[148:151], v[210:213], v[68:71]
	v_mfma_f32_16x16x32_bf16 v[100:103], v[156:159], v[164:167], v[100:103]
	v_mfma_f32_16x16x32_bf16 v[84:87], v[156:159], v[172:175], v[84:87]
	v_mfma_f32_16x16x32_bf16 v[72:75], v[156:159], v[202:205], v[72:75]
	v_mfma_f32_16x16x32_bf16 v[64:67], v[156:159], v[210:213], v[64:67]
	s_setprio 0
	s_barrier
; #define PG8_STAGE(bufoff, gbase, voff) do { _Pragma("unroll") for (int _i = 0; _i < 2; ++_i) \
;         __builtin_amdgcn_global_load_lds((const unsigned*)((const char*)(gbase) + (voff)[_i]), (LAS unsigned*)(lds + (bufoff) + ldsw + _i * 8192), 16, 0, 0); } while (0)
; #define PG8_LDA(dst, b, h) do { _Pragma("unroll") for (int m = 0; m < 4; ++m) _Pragma("unroll") for (int k = 0; k < 2; ++k) dst[m][k] = *(const LAS bf16x8*)(lds + PG8_SA(b, h) + aoff + m * 2048 + k * 1024); } while (0)
; #define PG8_MMA(ai, bj, At, Bt) do { __builtin_amdgcn_s_setprio(1); _Pragma("unroll") for (int m = 0; m < 4; ++m) _Pragma("unroll") for (int n = 0; n < 2; ++n) _Pragma("unroll") for (int k = 0; k < 2; ++k) \
;         acc[ai][bj][m][n] = __builtin_amdgcn_mfma_f32_16x16x32_bf16(Bt[n][k], At[m][k], acc[ai][bj][m][n], 0, 0, 0); __builtin_amdgcn_s_setprio(0); } while (0)
; #define PG8_WAIT_V(n) asm volatile("s_waitcnt vmcnt(" #n ")" ::: "memory")
; #define PG8_WAIT_L(n) asm volatile("s_waitcnt lgkmcnt(" #n ")" ::: "memory")
; #define PG8_BAR __builtin_amdgcn_s_barrier()
; #define PG8_SCHED __builtin_amdgcn_sched_barrier(0)
; template <class Epi, class Sched>
; __device__ __forceinline__ void gemm_phase(LAS unsigned char* lds, const Gemm g, const Sched& S, const Epi& E) {
;     ...
;             PG8_LDA(At, 1, 1); PG8_STAGE(PG8_SB(1, 0), b3, voffB); PG8_STAGE(PG8_SB(1, 1), b3 + hstep, voffB); PG8_STAGE(PG8_SA(1, 0), a3, voffA);
;             PG8_WAIT_V(8); PG8_WAIT_L(0); PG8_BAR; PG8_MMA(1, 0, At, B0); PG8_MMA(1, 1, At, B1); PG8_BAR; PG8_SCHED;
;         }
;         if (wr == 0) PG8_BAR;
	s_add_i32 s14, s17, s28
	v_lshl_add_u64 v[214:215], v[214:215], 0, s[84:85]
	s_mov_b32 m0, s14
	ds_read_b128 v[160:163], v232 offset:49152
	ds_read_b128 v[164:167], v232 offset:50176
	ds_read_b128 v[168:171], v232 offset:51200
	ds_read_b128 v[172:175], v232 offset:52224
	ds_read_b128 v[176:179], v232 offset:53248
	ds_read_b128 v[202:205], v232 offset:54272
	ds_read_b128 v[206:209], v232 offset:55296
	ds_read_b128 v[210:213], v232 offset:56320
	global_load_lds_dwordx4 v[214:215], off
	v_lshl_add_u64 v[214:215], v[216:217], 0, s[84:85]
	s_add_i32 m0, s14, 0x2000
	s_add_i32 s14, s33, s28
	global_load_lds_dwordx4 v[214:215], off
	v_lshl_add_u64 v[214:215], v[234:235], 0, s[84:85]
	s_mov_b32 m0, s14
	s_nop 0
	global_load_lds_dwordx4 v[214:215], off
	v_lshl_add_u64 v[214:215], v[236:237], 0, s[84:85]
	s_add_i32 m0, s14, 0x2000
	s_nop 0
	global_load_lds_dwordx4 v[214:215], off
	v_lshl_add_u64 v[214:215], v[238:239], 0, s[84:85]
	s_mov_b32 m0, s66
	s_nop 0
	global_load_lds_dwordx4 v[214:215], off
	v_lshl_add_u64 v[214:215], v[240:241], 0, s[84:85]
	s_mov_b32 m0, s67
	s_nop 0
	global_load_lds_dwordx4 v[214:215], off
	s_waitcnt vmcnt(8)
	s_waitcnt lgkmcnt(0)
	s_barrier
	s_setprio 1
	s_waitcnt lgkmcnt(0)
	v_mfma_f32_16x16x32_bf16 v[60:63], v[128:131], v[160:163], v[60:63]
	v_mfma_f32_16x16x32_bf16 v[52:55], v[128:131], v[168:171], v[52:55]
	v_mfma_f32_16x16x32_bf16 v[36:39], v[128:131], v[176:179], v[36:39]
	v_mfma_f32_16x16x32_bf16 v[20:23], v[128:131], v[206:209], v[20:23]
	v_mfma_f32_16x16x32_bf16 v[56:59], v[136:139], v[160:163], v[56:59]
	v_mfma_f32_16x16x32_bf16 v[48:51], v[136:139], v[168:171], v[48:51]
	v_mfma_f32_16x16x32_bf16 v[32:35], v[136:139], v[176:179], v[32:35]
	v_mfma_f32_16x16x32_bf16 v[16:19], v[136:139], v[206:209], v[16:19]
	v_mfma_f32_16x16x32_bf16 v[60:63], v[132:135], v[164:167], v[60:63]
	v_mfma_f32_16x16x32_bf16 v[52:55], v[132:135], v[172:175], v[52:55]
	v_mfma_f32_16x16x32_bf16 v[36:39], v[132:135], v[202:205], v[36:39]
	v_mfma_f32_16x16x32_bf16 v[20:23], v[132:135], v[210:213], v[20:23]
	v_mfma_f32_16x16x32_bf16 v[56:59], v[140:143], v[164:167], v[56:59]
	v_mfma_f32_16x16x32_bf16 v[48:51], v[140:143], v[172:175], v[48:51]
	v_mfma_f32_16x16x32_bf16 v[32:35], v[140:143], v[202:205], v[32:35]
	v_mfma_f32_16x16x32_bf16 v[16:19], v[140:143], v[210:213], v[16:19]
	s_setprio 0
	s_setprio 1
	v_mfma_f32_16x16x32_bf16 v[44:47], v[144:147], v[160:163], v[44:47]
	v_mfma_f32_16x16x32_bf16 v[28:31], v[144:147], v[168:171], v[28:31]
	v_mfma_f32_16x16x32_bf16 v[12:15], v[144:147], v[176:179], v[12:15]
	v_mfma_f32_16x16x32_bf16 v[4:7], v[144:147], v[206:209], v[4:7]
	v_mfma_f32_16x16x32_bf16 v[40:43], v[152:155], v[160:163], v[40:43]
	v_mfma_f32_16x16x32_bf16 v[24:27], v[152:155], v[168:171], v[24:27]
	v_mfma_f32_16x16x32_bf16 v[8:11], v[152:155], v[176:179], v[8:11]
	v_mfma_f32_16x16x32_bf16 v[0:3], v[152:155], v[206:209], v[0:3]
	v_mfma_f32_16x16x32_bf16 v[44:47], v[148:151], v[164:167], v[44:47]
	v_mfma_f32_16x16x32_bf16 v[28:31], v[148:151], v[172:175], v[28:31]
	v_mfma_f32_16x16x32_bf16 v[12:15], v[148:151], v[202:205], v[12:15]
	v_mfma_f32_16x16x32_bf16 v[4:7], v[148:151], v[210:213], v[4:7]
	v_mfma_f32_16x16x32_bf16 v[40:43], v[156:159], v[164:167], v[40:43]
	v_mfma_f32_16x16x32_bf16 v[24:27], v[156:159], v[172:175], v[24:27]
	v_mfma_f32_16x16x32_bf16 v[8:11], v[156:159], v[202:205], v[8:11]
	v_mfma_f32_16x16x32_bf16 v[0:3], v[156:159], v[210:213], v[0:3]
	s_setprio 0
	s_barrier
	s_add_u32 s6, s6, 0x100
	s_addc_u32 s7, s7, 0
	s_add_u32 s13, s13, 0x100
	s_addc_u32 s16, s16, 0
	s_cmp_ge_u32 s19, s8
	s_mov_b32 s17, s19
	s_cbranch_scc0 .LBB0_599
	s_and_b64 vcc, exec, s[62:63]
	s_cbranch_vccz .LBB0_602
	s_barrier

; #define PG8_STAGE(bufoff, gbase, voff) do { _Pragma("unroll") for (int _i = 0; _i < 2; ++_i) \
;         __builtin_amdgcn_global_load_lds((const unsigned*)((const char*)(gbase) + (voff)[_i]), (LAS unsigned*)(lds + (bufoff) + ldsw + _i * 8192), 16, 0, 0); } while (0)
; #define PG8_LDA(dst, b, h) do { _Pragma("unroll") for (int m = 0; m < 4; ++m) _Pragma("unroll") for (int k = 0; k < 2; ++k) dst[m][k] = *(const LAS bf16x8*)(lds + PG8_SA(b, h) + aoff + m * 2048 + k * 1024); } while (0)
; #define PG8_LDB(dst, b, h) do { _Pragma("unroll") for (int n = 0; n < 2; ++n) _Pragma("unroll") for (int k = 0; k < 2; ++k) dst[n][k] = *(const LAS bf16x8*)(lds + PG8_SB(b, h) + boff + n * 2048 + k * 1024); } while (0)
; #define PG8_MMA(ai, bj, At, Bt) do { __builtin_amdgcn_s_setprio(1); _Pragma("unroll") for (int m = 0; m < 4; ++m) _Pragma("unroll") for (int n = 0; n < 2; ++n) _Pragma("unroll") for (int k = 0; k < 2; ++k) \
;         acc[ai][bj][m][n] = __builtin_amdgcn_mfma_f32_16x16x32_bf16(Bt[n][k], At[m][k], acc[ai][bj][m][n], 0, 0, 0); __builtin_amdgcn_s_setprio(0); } while (0)
; #define PG8_WAIT_V(n) asm volatile("s_waitcnt vmcnt(" #n ")" ::: "memory")
; #define PG8_WAIT_L(n) asm volatile("s_waitcnt lgkmcnt(" #n ")" ::: "memory")
; #define PG8_BAR __builtin_amdgcn_s_barrier()
; #define PG8_SCHED __builtin_amdgcn_sched_barrier(0)
; template <class Epi, class Sched>
; __device__ __forceinline__ void gemm_phase(LAS unsigned char* lds, const Gemm g, const Sched& S, const Epi& E) {
;     ...
;         for (int t = 0; t < nt; t += 2) {
;             const bool last = (t == nt - 2);
;             const char* a1 = cA + (size_t)(t + 1) * kstep;
;             const char* a2 = last ? nA : cA + (size_t)(t + 2) * kstep; const char* b2 = last ? nB : cB + (size_t)(t + 2) * kstep;
;             const char* a3 = a2 + kstep; const char* b3 = b2 + kstep;
;             PG8_LDB(B0, 0, 0); PG8_LDB(B1, 0, 1); PG8_SCHED; PG8_LDA(At, 0, 0); PG8_STAGE(PG8_SA(1, 1), a1 + hstep, voffA);
;             PG8_WAIT_V(8); PG8_WAIT_L(0); PG8_BAR; PG8_MMA(0, 0, At, B0); PG8_MMA(0, 1, At, B1); PG8_BAR; PG8_SCHED;
;             PG8_LDA(At, 0, 1); PG8_STAGE(PG8_SB(0, 0), b2, voffB); PG8_STAGE(PG8_SB(0, 1), b2 + hstep, voffB); PG8_STAGE(PG8_SA(0, 0), a2, voffA);
.LBB0_744:
	s_add_u32 s24, s22, 0xfffc0080
	s_addc_u32 s25, s23, -1
	s_add_i32 s49, 0, 0x10000
	s_cmp_eq_u32 s48, 12
	s_cselect_b32 s27, s15, s25
	s_cselect_b32 s26, s44, s24
	s_cselect_b32 s25, s17, s47
	s_cselect_b32 s24, s45, s46
	s_add_i32 s52, 0, 0x14000
	v_add_u32_e32 v140, s49, v162
	v_add_u32_e32 v158, s52, v162
	ds_read_b128 v[128:131], v140
	ds_read_b128 v[132:135], v140 offset:1024
	ds_read_b128 v[136:139], v140 offset:2048
	ds_read_b128 v[140:143], v140 offset:3072
	ds_read_b128 v[154:157], v158
	ds_read_b128 v[164:167], v158 offset:1024
	ds_read_b128 v[168:171], v158 offset:2048
	ds_read_b128 v[172:175], v158 offset:3072
	v_lshl_add_u64 v[158:159], s[22:23], 0, v[150:151]
	s_add_i32 m0, s28, 0xc000
	ds_read_b128 v[176:179], v163
	ds_read_b128 v[192:195], v163 offset:1024
	ds_read_b128 v[196:199], v163 offset:2048
	ds_read_b128 v[200:203], v163 offset:3072
	ds_read_b128 v[204:207], v163 offset:4096
	ds_read_b128 v[208:211], v163 offset:5120
	ds_read_b128 v[212:215], v163 offset:6144
	ds_read_b128 v[230:233], v163 offset:7168
	global_load_lds_dwordx4 v[158:159], off
	v_lshl_add_u64 v[158:159], s[22:23], 0, v[152:153]
	s_add_i32 m0, s28, 0xe000
	s_nop 0
	global_load_lds_dwordx4 v[158:159], off
	s_waitcnt vmcnt(8)
	s_waitcnt lgkmcnt(0)
	s_barrier
	s_setprio 1
	s_waitcnt lgkmcnt(0)
	v_mfma_f32_16x16x32_bf16 v[124:127], v[128:131], v[176:179], v[124:127]
	v_mfma_f32_16x16x32_bf16 v[108:111], v[128:131], v[196:199], v[108:111]
	v_mfma_f32_16x16x32_bf16 v[92:95], v[128:131], v[204:207], v[92:95]
	v_mfma_f32_16x16x32_bf16 v[76:79], v[128:131], v[212:215], v[76:79]
	v_mfma_f32_16x16x32_bf16 v[120:123], v[136:139], v[176:179], v[120:123]
	v_mfma_f32_16x16x32_bf16 v[104:107], v[136:139], v[196:199], v[104:107]
	v_mfma_f32_16x16x32_bf16 v[88:91], v[136:139], v[204:207], v[88:91]
	v_mfma_f32_16x16x32_bf16 v[72:75], v[136:139], v[212:215], v[72:75]
	v_mfma_f32_16x16x32_bf16 v[124:127], v[132:135], v[192:195], v[124:127]
	v_mfma_f32_16x16x32_bf16 v[108:111], v[132:135], v[200:203], v[108:111]
	v_mfma_f32_16x16x32_bf16 v[92:95], v[132:135], v[208:211], v[92:95]
	v_mfma_f32_16x16x32_bf16 v[76:79], v[132:135], v[230:233], v[76:79]
	v_mfma_f32_16x16x32_bf16 v[120:123], v[140:143], v[192:195], v[120:123]
	v_mfma_f32_16x16x32_bf16 v[104:107], v[140:143], v[200:203], v[104:107]
	v_mfma_f32_16x16x32_bf16 v[88:91], v[140:143], v[208:211], v[88:91]
	v_mfma_f32_16x16x32_bf16 v[72:75], v[140:143], v[230:233], v[72:75]
	s_setprio 0
	s_setprio 1
	v_mfma_f32_16x16x32_bf16 v[112:115], v[154:157], v[176:179], v[112:115]
	v_mfma_f32_16x16x32_bf16 v[96:99], v[154:157], v[196:199], v[96:99]
	v_mfma_f32_16x16x32_bf16 v[80:83], v[154:157], v[204:207], v[80:83]
	v_mfma_f32_16x16x32_bf16 v[64:67], v[154:157], v[212:215], v[64:67]
	v_mfma_f32_16x16x32_bf16 v[116:119], v[168:171], v[176:179], v[116:119]
	v_mfma_f32_16x16x32_bf16 v[100:103], v[168:171], v[196:199], v[100:103]
	v_mfma_f32_16x16x32_bf16 v[84:87], v[168:171], v[204:207], v[84:87]
	v_mfma_f32_16x16x32_bf16 v[68:71], v[168:171], v[212:215], v[68:71]
	v_mfma_f32_16x16x32_bf16 v[112:115], v[164:167], v[192:195], v[112:115]
	v_mfma_f32_16x16x32_bf16 v[96:99], v[164:167], v[200:203], v[96:99]
	v_mfma_f32_16x16x32_bf16 v[80:83], v[164:167], v[208:211], v[80:83]
	v_mfma_f32_16x16x32_bf16 v[64:67], v[164:167], v[230:233], v[64:67]
	v_mfma_f32_16x16x32_bf16 v[116:119], v[172:175], v[192:195], v[116:119]
	v_mfma_f32_16x16x32_bf16 v[100:103], v[172:175], v[200:203], v[100:103]
	v_mfma_f32_16x16x32_bf16 v[84:87], v[172:175], v[208:211], v[84:87]
	v_mfma_f32_16x16x32_bf16 v[68:71], v[172:175], v[230:233], v[68:71]
	s_setprio 0
	s_barrier
	s_add_i32 s49, s49, s8
	v_lshl_add_u64 v[158:159], s[24:25], 0, v[184:185]
	s_mov_b32 m0, s49
	ds_read_b128 v[176:179], v163 offset:16384
	ds_read_b128 v[192:195], v163 offset:17408
	ds_read_b128 v[196:199], v163 offset:18432
	ds_read_b128 v[200:203], v163 offset:19456
	ds_read_b128 v[204:207], v163 offset:20480
	ds_read_b128 v[208:211], v163 offset:21504
	ds_read_b128 v[212:215], v163 offset:22528
	ds_read_b128 v[230:233], v163 offset:23552
	global_load_lds_dwordx4 v[158:159], off
	s_add_i32 m0, s49, 0x2000
	s_add_u32 s50, s24, 0x40000
	v_lshl_add_u64 v[216:217], s[24:25], 0, v[144:145]
	s_addc_u32 s51, s25, 0
	s_add_i32 s49, s52, s8
	global_load_lds_dwordx4 v[216:217], off
	v_lshl_add_u64 v[234:235], s[50:51], 0, v[184:185]
	s_mov_b32 m0, s49
	v_lshl_add_u64 v[236:237], s[26:27], 0, v[146:147]
	global_load_lds_dwordx4 v[234:235], off
	v_lshl_add_u64 v[234:235], s[50:51], 0, v[144:145]
	s_add_i32 m0, s49, 0x2000
	s_nop 0
	global_load_lds_dwordx4 v[234:235], off
	v_lshl_add_u64 v[234:235], s[26:27], 0, v[148:149]
	s_mov_b32 m0, s28
	s_nop 0
	global_load_lds_dwordx4 v[234:235], off
	s_mov_b32 m0, s29
	s_nop 0
	global_load_lds_dwordx4 v[236:237], off
	s_waitcnt vmcnt(8)
	s_waitcnt lgkmcnt(0)
	s_barrier
; #define PG8_STAGE(bufoff, gbase, voff) do { _Pragma("unroll") for (int _i = 0; _i < 2; ++_i) \
;         __builtin_amdgcn_global_load_lds((const unsigned*)((const char*)(gbase) + (voff)[_i]), (LAS unsigned*)(lds + (bufoff) + ldsw + _i * 8192), 16, 0, 0); } while (0)
; #define PG8_LDA(dst, b, h) do { _Pragma("unroll") for (int m = 0; m < 4; ++m) _Pragma("unroll") for (int k = 0; k < 2; ++k) dst[m][k] = *(const LAS bf16x8*)(lds + PG8_SA(b, h) + aoff + m * 2048 + k * 1024); } while (0)
; #define PG8_LDB(dst, b, h) do { _Pragma("unroll") for (int n = 0; n < 2; ++n) _Pragma("unroll") for (int k = 0; k < 2; ++k) dst[n][k] = *(const LAS bf16x8*)(lds + PG8_SB(b, h) + boff + n * 2048 + k * 1024); } while (0)
; #define PG8_MMA(ai, bj, At, Bt) do { __builtin_amdgcn_s_setprio(1); _Pragma("unroll") for (int m = 0; m < 4; ++m) _Pragma("unroll") for (int n = 0; n < 2; ++n) _Pragma("unroll") for (int k = 0; k < 2; ++k) \
;         acc[ai][bj][m][n] = __builtin_amdgcn_mfma_f32_16x16x32_bf16(Bt[n][k], At[m][k], acc[ai][bj][m][n], 0, 0, 0); __builtin_amdgcn_s_setprio(0); } while (0)
; #define PG8_WAIT_V(n) asm volatile("s_waitcnt vmcnt(" #n ")" ::: "memory")
; #define PG8_WAIT_L(n) asm volatile("s_waitcnt lgkmcnt(" #n ")" ::: "memory")
; #define PG8_BAR __builtin_amdgcn_s_barrier()
; #define PG8_SCHED __builtin_amdgcn_sched_barrier(0)
; template <class Epi, class Sched>
; __device__ __forceinline__ void gemm_phase(LAS unsigned char* lds, const Gemm g, const Sched& S, const Epi& E) {
;     ...
;             PG8_WAIT_V(8); PG8_WAIT_L(0); PG8_BAR; PG8_MMA(1, 0, At, B0); PG8_MMA(1, 1, At, B1); PG8_BAR; PG8_SCHED;
;             PG8_LDB(B0, 1, 0); PG8_LDB(B1, 1, 1); PG8_SCHED; PG8_LDA(At, 1, 0); PG8_STAGE(PG8_SA(0, 1), a2 + hstep, voffA);
;             PG8_WAIT_V(8); PG8_WAIT_L(0); PG8_BAR; PG8_MMA(0, 0, At, B0); PG8_MMA(0, 1, At, B1); PG8_BAR; PG8_SCHED;
	s_setprio 1
	s_waitcnt lgkmcnt(0)
	v_mfma_f32_16x16x32_bf16 v[60:63], v[128:131], v[176:179], v[60:63]
	v_mfma_f32_16x16x32_bf16 v[44:47], v[128:131], v[196:199], v[44:47]
	v_mfma_f32_16x16x32_bf16 v[28:31], v[128:131], v[204:207], v[28:31]
	v_mfma_f32_16x16x32_bf16 v[12:15], v[128:131], v[212:215], v[12:15]
	v_mfma_f32_16x16x32_bf16 v[56:59], v[136:139], v[176:179], v[56:59]
	v_mfma_f32_16x16x32_bf16 v[40:43], v[136:139], v[196:199], v[40:43]
	v_mfma_f32_16x16x32_bf16 v[24:27], v[136:139], v[204:207], v[24:27]
	v_mfma_f32_16x16x32_bf16 v[8:11], v[136:139], v[212:215], v[8:11]
	v_mfma_f32_16x16x32_bf16 v[60:63], v[132:135], v[192:195], v[60:63]
	v_mfma_f32_16x16x32_bf16 v[44:47], v[132:135], v[200:203], v[44:47]
	v_mfma_f32_16x16x32_bf16 v[28:31], v[132:135], v[208:211], v[28:31]
	v_mfma_f32_16x16x32_bf16 v[12:15], v[132:135], v[230:233], v[12:15]
	v_mfma_f32_16x16x32_bf16 v[56:59], v[140:143], v[192:195], v[56:59]
	v_mfma_f32_16x16x32_bf16 v[40:43], v[140:143], v[200:203], v[40:43]
	v_mfma_f32_16x16x32_bf16 v[24:27], v[140:143], v[208:211], v[24:27]
	v_mfma_f32_16x16x32_bf16 v[8:11], v[140:143], v[230:233], v[8:11]
	s_setprio 0
	s_setprio 1
	v_mfma_f32_16x16x32_bf16 v[48:51], v[154:157], v[176:179], v[48:51]
	v_mfma_f32_16x16x32_bf16 v[32:35], v[154:157], v[196:199], v[32:35]
	v_mfma_f32_16x16x32_bf16 v[16:19], v[154:157], v[204:207], v[16:19]
	v_mfma_f32_16x16x32_bf16 v[0:3], v[154:157], v[212:215], v[0:3]
	v_mfma_f32_16x16x32_bf16 v[52:55], v[168:171], v[176:179], v[52:55]
	v_mfma_f32_16x16x32_bf16 v[36:39], v[168:171], v[196:199], v[36:39]
	v_mfma_f32_16x16x32_bf16 v[20:23], v[168:171], v[204:207], v[20:23]
	v_mfma_f32_16x16x32_bf16 v[4:7], v[168:171], v[212:215], v[4:7]
	v_mfma_f32_16x16x32_bf16 v[48:51], v[164:167], v[192:195], v[48:51]
	v_mfma_f32_16x16x32_bf16 v[32:35], v[164:167], v[200:203], v[32:35]
	v_mfma_f32_16x16x32_bf16 v[16:19], v[164:167], v[208:211], v[16:19]
	v_mfma_f32_16x16x32_bf16 v[0:3], v[164:167], v[230:233], v[0:3]
	v_mfma_f32_16x16x32_bf16 v[52:55], v[172:175], v[192:195], v[52:55]
	v_mfma_f32_16x16x32_bf16 v[36:39], v[172:175], v[200:203], v[36:39]
	v_mfma_f32_16x16x32_bf16 v[20:23], v[172:175], v[208:211], v[20:23]
	v_mfma_f32_16x16x32_bf16 v[4:7], v[172:175], v[230:233], v[4:7]
	s_setprio 0
	s_barrier
	s_add_i32 s49, 0, 0x18000
	s_add_i32 s50, 0, 0x1c000
	v_add_u32_e32 v140, s49, v162
	v_add_u32_e32 v172, s50, v162
	ds_read_b128 v[128:131], v140
	ds_read_b128 v[132:135], v140 offset:1024
	ds_read_b128 v[136:139], v140 offset:2048
	ds_read_b128 v[140:143], v140 offset:3072
	ds_read_b128 v[154:157], v172
	ds_read_b128 v[164:167], v172 offset:1024
	ds_read_b128 v[168:171], v172 offset:2048
	ds_read_b128 v[172:175], v172 offset:3072
	s_add_u32 s26, s26, 0x40000
	s_addc_u32 s27, s27, 0
	s_mov_b32 m0, s30
	v_lshl_add_u64 v[238:239], s[26:27], 0, v[148:149]
	ds_read_b128 v[176:179], v163 offset:32768
	ds_read_b128 v[192:195], v163 offset:33792
	ds_read_b128 v[196:199], v163 offset:34816
	ds_read_b128 v[200:203], v163 offset:35840
	ds_read_b128 v[204:207], v163 offset:36864
	ds_read_b128 v[208:211], v163 offset:37888
	ds_read_b128 v[212:215], v163 offset:38912
	ds_read_b128 v[230:233], v163 offset:39936
	global_load_lds_dwordx4 v[238:239], off
	v_lshl_add_u64 v[238:239], s[26:27], 0, v[146:147]
	s_mov_b32 m0, s31
	s_nop 0
	global_load_lds_dwordx4 v[238:239], off
	s_waitcnt vmcnt(8)
	s_waitcnt lgkmcnt(0)
	s_barrier
	s_setprio 1
	s_waitcnt lgkmcnt(0)
	v_mfma_f32_16x16x32_bf16 v[124:127], v[128:131], v[176:179], v[124:127]
	v_mfma_f32_16x16x32_bf16 v[108:111], v[128:131], v[196:199], v[108:111]
	v_mfma_f32_16x16x32_bf16 v[92:95], v[128:131], v[204:207], v[92:95]
	v_mfma_f32_16x16x32_bf16 v[76:79], v[128:131], v[212:215], v[76:79]
	v_mfma_f32_16x16x32_bf16 v[120:123], v[136:139], v[176:179], v[120:123]
	v_mfma_f32_16x16x32_bf16 v[104:107], v[136:139], v[196:199], v[104:107]
	v_mfma_f32_16x16x32_bf16 v[88:91], v[136:139], v[204:207], v[88:91]
	v_mfma_f32_16x16x32_bf16 v[72:75], v[136:139], v[212:215], v[72:75]
	v_mfma_f32_16x16x32_bf16 v[124:127], v[132:135], v[192:195], v[124:127]
	v_mfma_f32_16x16x32_bf16 v[108:111], v[132:135], v[200:203], v[108:111]
	v_mfma_f32_16x16x32_bf16 v[92:95], v[132:135], v[208:211], v[92:95]
	v_mfma_f32_16x16x32_bf16 v[76:79], v[132:135], v[230:233], v[76:79]
	v_mfma_f32_16x16x32_bf16 v[120:123], v[140:143], v[192:195], v[120:123]
	v_mfma_f32_16x16x32_bf16 v[104:107], v[140:143], v[200:203], v[104:107]
	v_mfma_f32_16x16x32_bf16 v[88:91], v[140:143], v[208:211], v[88:91]
	v_mfma_f32_16x16x32_bf16 v[72:75], v[140:143], v[230:233], v[72:75]
	s_setprio 0
	s_setprio 1
	v_mfma_f32_16x16x32_bf16 v[112:115], v[154:157], v[176:179], v[112:115]
	v_mfma_f32_16x16x32_bf16 v[96:99], v[154:157], v[196:199], v[96:99]
	v_mfma_f32_16x16x32_bf16 v[80:83], v[154:157], v[204:207], v[80:83]
	v_mfma_f32_16x16x32_bf16 v[64:67], v[154:157], v[212:215], v[64:67]
	v_mfma_f32_16x16x32_bf16 v[116:119], v[168:171], v[176:179], v[116:119]
	v_mfma_f32_16x16x32_bf16 v[100:103], v[168:171], v[196:199], v[100:103]
	v_mfma_f32_16x16x32_bf16 v[84:87], v[168:171], v[204:207], v[84:87]
	v_mfma_f32_16x16x32_bf16 v[68:71], v[168:171], v[212:215], v[68:71]
	v_mfma_f32_16x16x32_bf16 v[112:115], v[164:167], v[192:195], v[112:115]
	v_mfma_f32_16x16x32_bf16 v[96:99], v[164:167], v[200:203], v[96:99]
	v_mfma_f32_16x16x32_bf16 v[80:83], v[164:167], v[208:211], v[80:83]
	v_mfma_f32_16x16x32_bf16 v[64:67], v[164:167], v[230:233], v[64:67]
	v_mfma_f32_16x16x32_bf16 v[116:119], v[172:175], v[192:195], v[116:119]
	v_mfma_f32_16x16x32_bf16 v[100:103], v[172:175], v[200:203], v[100:103]
	v_mfma_f32_16x16x32_bf16 v[84:87], v[172:175], v[208:211], v[84:87]
	v_mfma_f32_16x16x32_bf16 v[68:71], v[172:175], v[230:233], v[68:71]
	s_setprio 0
	s_barrier
; #define PG8_STAGE(bufoff, gbase, voff) do { _Pragma("unroll") for (int _i = 0; _i < 2; ++_i) \
;         __builtin_amdgcn_global_load_lds((const unsigned*)((const char*)(gbase) + (voff)[_i]), (LAS unsigned*)(lds + (bufoff) + ldsw + _i * 8192), 16, 0, 0); } while (0)
; #define PG8_LDA(dst, b, h) do { _Pragma("unroll") for (int m = 0; m < 4; ++m) _Pragma("unroll") for (int k = 0; k < 2; ++k) dst[m][k] = *(const LAS bf16x8*)(lds + PG8_SA(b, h) + aoff + m * 2048 + k * 1024); } while (0)
; #define PG8_MMA(ai, bj, At, Bt) do { __builtin_amdgcn_s_setprio(1); _Pragma("unroll") for (int m = 0; m < 4; ++m) _Pragma("unroll") for (int n = 0; n < 2; ++n) _Pragma("unroll") for (int k = 0; k < 2; ++k) \
;         acc[ai][bj][m][n] = __builtin_amdgcn_mfma_f32_16x16x32_bf16(Bt[n][k], At[m][k], acc[ai][bj][m][n], 0, 0, 0); __builtin_amdgcn_s_setprio(0); } while (0)
; #define PG8_WAIT_V(n) asm volatile("s_waitcnt vmcnt(" #n ")" ::: "memory")
; #define PG8_WAIT_L(n) asm volatile("s_waitcnt lgkmcnt(" #n ")" ::: "memory")
; #define PG8_BAR __builtin_amdgcn_s_barrier()
; #define PG8_SCHED __builtin_amdgcn_sched_barrier(0)
; template <class Epi, class Sched>
; __device__ __forceinline__ void gemm_phase(LAS unsigned char* lds, const Gemm g, const Sched& S, const Epi& E) {
;     ...
;             PG8_LDA(At, 1, 1); PG8_STAGE(PG8_SB(1, 0), b3, voffB); PG8_STAGE(PG8_SB(1, 1), b3 + hstep, voffB); PG8_STAGE(PG8_SA(1, 0), a3, voffA);
;             PG8_WAIT_V(8); PG8_WAIT_L(0); PG8_BAR; PG8_MMA(1, 0, At, B0); PG8_MMA(1, 1, At, B1); PG8_BAR; PG8_SCHED;
;         }
;         if (wr == 0) PG8_BAR;
	s_add_i32 s26, s49, s8
	v_lshl_add_u64 v[158:159], v[158:159], 0, s[84:85]
	s_mov_b32 m0, s26
	ds_read_b128 v[176:179], v163 offset:49152
	ds_read_b128 v[192:195], v163 offset:50176
	ds_read_b128 v[196:199], v163 offset:51200
	ds_read_b128 v[200:203], v163 offset:52224
	ds_read_b128 v[204:207], v163 offset:53248
	ds_read_b128 v[208:211], v163 offset:54272
	ds_read_b128 v[212:215], v163 offset:55296
	ds_read_b128 v[230:233], v163 offset:56320
	global_load_lds_dwordx4 v[158:159], off
	s_add_i32 m0, s26, 0x2000
	s_add_u32 s24, s24, 0x40080
	v_lshl_add_u64 v[158:159], v[216:217], 0, s[84:85]
	s_addc_u32 s25, s25, 0
	s_add_i32 s26, s50, s8
	global_load_lds_dwordx4 v[158:159], off
	v_lshl_add_u64 v[158:159], s[24:25], 0, v[184:185]
	s_mov_b32 m0, s26
	s_nop 0
	global_load_lds_dwordx4 v[158:159], off
	v_lshl_add_u64 v[158:159], s[24:25], 0, v[144:145]
	s_add_i32 m0, s26, 0x2000
	s_nop 0
	global_load_lds_dwordx4 v[158:159], off
	v_lshl_add_u64 v[158:159], v[234:235], 0, s[84:85]
	s_mov_b32 m0, s36
	s_nop 0
	global_load_lds_dwordx4 v[158:159], off
	v_lshl_add_u64 v[158:159], v[236:237], 0, s[84:85]
	s_mov_b32 m0, s37
	s_nop 0
	global_load_lds_dwordx4 v[158:159], off
	s_waitcnt vmcnt(8)
	s_waitcnt lgkmcnt(0)
	s_barrier
	s_setprio 1
	s_waitcnt lgkmcnt(0)
	v_mfma_f32_16x16x32_bf16 v[60:63], v[128:131], v[176:179], v[60:63]
	v_mfma_f32_16x16x32_bf16 v[44:47], v[128:131], v[196:199], v[44:47]
	v_mfma_f32_16x16x32_bf16 v[28:31], v[128:131], v[204:207], v[28:31]
	v_mfma_f32_16x16x32_bf16 v[12:15], v[128:131], v[212:215], v[12:15]
	v_mfma_f32_16x16x32_bf16 v[56:59], v[136:139], v[176:179], v[56:59]
	v_mfma_f32_16x16x32_bf16 v[40:43], v[136:139], v[196:199], v[40:43]
	v_mfma_f32_16x16x32_bf16 v[24:27], v[136:139], v[204:207], v[24:27]
	v_mfma_f32_16x16x32_bf16 v[8:11], v[136:139], v[212:215], v[8:11]
	v_mfma_f32_16x16x32_bf16 v[60:63], v[132:135], v[192:195], v[60:63]
	v_mfma_f32_16x16x32_bf16 v[44:47], v[132:135], v[200:203], v[44:47]
	v_mfma_f32_16x16x32_bf16 v[28:31], v[132:135], v[208:211], v[28:31]
	v_mfma_f32_16x16x32_bf16 v[12:15], v[132:135], v[230:233], v[12:15]
	v_mfma_f32_16x16x32_bf16 v[56:59], v[140:143], v[192:195], v[56:59]
	v_mfma_f32_16x16x32_bf16 v[40:43], v[140:143], v[200:203], v[40:43]
	v_mfma_f32_16x16x32_bf16 v[24:27], v[140:143], v[208:211], v[24:27]
	v_mfma_f32_16x16x32_bf16 v[8:11], v[140:143], v[230:233], v[8:11]
	s_setprio 0
	s_setprio 1
	v_mfma_f32_16x16x32_bf16 v[48:51], v[154:157], v[176:179], v[48:51]
	v_mfma_f32_16x16x32_bf16 v[32:35], v[154:157], v[196:199], v[32:35]
	v_mfma_f32_16x16x32_bf16 v[16:19], v[154:157], v[204:207], v[16:19]
	v_mfma_f32_16x16x32_bf16 v[0:3], v[154:157], v[212:215], v[0:3]
	v_mfma_f32_16x16x32_bf16 v[52:55], v[168:171], v[176:179], v[52:55]
	v_mfma_f32_16x16x32_bf16 v[36:39], v[168:171], v[196:199], v[36:39]
	v_mfma_f32_16x16x32_bf16 v[20:23], v[168:171], v[204:207], v[20:23]
	v_mfma_f32_16x16x32_bf16 v[4:7], v[168:171], v[212:215], v[4:7]
	v_mfma_f32_16x16x32_bf16 v[48:51], v[164:167], v[192:195], v[48:51]
	v_mfma_f32_16x16x32_bf16 v[32:35], v[164:167], v[200:203], v[32:35]
	v_mfma_f32_16x16x32_bf16 v[16:19], v[164:167], v[208:211], v[16:19]
	v_mfma_f32_16x16x32_bf16 v[0:3], v[164:167], v[230:233], v[0:3]
	v_mfma_f32_16x16x32_bf16 v[52:55], v[172:175], v[192:195], v[52:55]
	v_mfma_f32_16x16x32_bf16 v[36:39], v[172:175], v[200:203], v[36:39]
	v_mfma_f32_16x16x32_bf16 v[20:23], v[172:175], v[208:211], v[20:23]
	v_mfma_f32_16x16x32_bf16 v[4:7], v[172:175], v[230:233], v[4:7]
	s_setprio 0
	s_barrier
	s_add_i32 s48, s48, 2
	s_add_u32 s22, s22, 0x100
	s_addc_u32 s23, s23, 0
	s_add_u32 s46, s46, 0x100
	s_addc_u32 s47, s47, 0
	s_cmp_gt_u32 s48, 13
	s_cbranch_scc0 .LBB0_744
	s_and_b64 vcc, exec, s[6:7]
	s_cbranch_vccz .LBB0_747
	s_barrier
